# phase-14 epilogue: permlane16_swap pairs -> dwordx4 stores (lever 7.3)
# speedup vs baseline: 1.0088x; 1.0034x over previous
.Lrms_done:
	s_cmpk_gt_i32 s10, 0x267f
	v_and_b32_e32 v34, 63, v0
	s_cbranch_scc1 .LBB0_78
	s_mov_b64 exec, -1
	v_readlane_b32 s0, v254, 0
	v_readlane_b32 s1, v254, 1
	s_nop 4
	s_load_dwordx2 s[56:57], s[0:1], 0x50
	s_load_dwordx2 s[58:59], s[0:1], 0x98
	s_load_dwordx2 s[60:61], s[0:1], 0x60
	s_load_dwordx2 s[62:63], s[0:1], 0xd8
	s_load_dwordx2 s[64:65], s[0:1], 0x48
	v_readfirstlane_b32 s4, v0
	v_and_b32_e32 v7, 63, v0
	s_lshr_b32 s4, s4, 6
	v_lshrrev_b32_e32 v1, 3, v7
	v_and_b32_e32 v2, 7, v7
	s_lshl_b32 s5, s4, 14
	v_lshlrev_b32_e32 v5, 5, v2
	s_movk_i32 s18, 0x420
	v_mul_u32_u24_e32 v4, s18, v2
	v_lshlrev_b32_e32 v2, 4, v2
	s_movk_i32 s18, 0x84
	v_mad_u32_u24 v3, v1, s18, v2
	v_lshl_add_u32 v4, v1, 2, v4
	v_add_u32_e32 v3, s5, v3
	v_add_u32_e32 v4, s5, v4
	v_mov_b32_e32 v148, v3
	v_add_u32_e32 v149, 1056, v3
	v_add_u32_e32 v150, 2112, v3
	v_add_u32_e32 v151, 3168, v3
	v_add_u32_e32 v152, 4224, v3
	v_add_u32_e32 v153, 5280, v3
	v_add_u32_e32 v154, 6336, v3
	v_add_u32_e32 v155, 7392, v3
	s_waitcnt lgkmcnt(0)
	s_mov_b32 s20, s10
	s_mov_b32 s21, s3
	s_mov_b32 s19, 0x2680
	s_cmp_ge_u32 s20, s19
	s_cbranch_scc1 .LBB0_78
	s_mov_b32 s26, s20
	s_cmp_lt_u32 s26, 0x2080
	s_cbranch_scc1 .Ltrp0_i1_s0
	s_sub_u32 s26, s26, 0x2080
	s_cmp_lt_u32 s26, 0x400
	s_cbranch_scc1 .Ltrp0_i1_s1
	s_sub_u32 s26, s26, 0x400
	s_cmp_lt_u32 s26, 0x100
	s_cbranch_scc1 .Ltrp0_i1_s2
	s_sub_u32 s26, s26, 0x100
	s_branch .Ltrp0_i1_s3

.Ltrp0_i1_c:
	s_lshl_b32 s4, s24, 6
	s_mul_i32 s4, s25, s4
	s_lshl_b32 s5, s27, 7
	s_add_u32 s4, s4, s5
	s_add_u32 s14, s22, s4
	s_addc_u32 s15, s23, 0
	v_mad_u32_u24 v6, v1, s24, v2
	s_lshl_b32 s4, s29, 5
	s_mul_i32 s4, s27, s4
	s_lshl_b32 s5, s25, 7
	s_add_u32 s4, s4, s5
	s_add_u32 s4, s4, s28
	s_add_u32 s34, s62, s4
	s_addc_u32 s35, s63, 0
	s_mov_b32 s36, s29
	s_mov_b32 s37, s31
	s_lshl_b32 s4, s25, 8
	s_add_u32 s4, s4, s30
	s_add_u32 s16, s64, s4
	s_addc_u32 s17, s65, 0
	s_lshl_b32 s18, s24, 3
	global_load_dwordx4 v[68:71], v6, s[14:15]
	s_add_u32 s14, s14, s18
	s_addc_u32 s15, s15, 0
	global_load_dwordx4 v[72:75], v6, s[14:15]
	s_add_u32 s14, s14, s18
	s_addc_u32 s15, s15, 0
	global_load_dwordx4 v[76:79], v6, s[14:15]
	s_add_u32 s14, s14, s18
	s_addc_u32 s15, s15, 0
	global_load_dwordx4 v[80:83], v6, s[14:15]
	s_add_u32 s14, s14, s18
	s_addc_u32 s15, s15, 0
	global_load_dwordx4 v[84:87], v6, s[14:15]
	s_add_u32 s14, s14, s18
	s_addc_u32 s15, s15, 0
	global_load_dwordx4 v[88:91], v6, s[14:15]
	s_add_u32 s14, s14, s18
	s_addc_u32 s15, s15, 0
	global_load_dwordx4 v[92:95], v6, s[14:15]
	s_add_u32 s14, s14, s18
	s_addc_u32 s15, s15, 0
	global_load_dwordx4 v[96:99], v6, s[14:15]
	global_load_dwordx4 v[100:103], v5, s[16:17]
	global_load_dwordx4 v[104:107], v5, s[16:17] offset:16
	s_add_u32 s20, s20, s21
	s_cmp_ge_u32 s20, s19
	s_mov_b32 s43, 0
	s_cbranch_scc1 .Ltrp0_pro_nob
	s_mov_b32 s26, s20
	s_cmp_lt_u32 s26, 0x2080
	s_cbranch_scc1 .Ltrp0_i2_s0
	s_sub_u32 s26, s26, 0x2080
	s_cmp_lt_u32 s26, 0x400
	s_cbranch_scc1 .Ltrp0_i2_s1
	s_sub_u32 s26, s26, 0x400
	s_cmp_lt_u32 s26, 0x100
	s_cbranch_scc1 .Ltrp0_i2_s2
	s_sub_u32 s26, s26, 0x100
	s_branch .Ltrp0_i2_s3

.Ltrp0_p3_ng:
	v_cvt_pk_bf16_f32 v36, v36, v37
	v_cvt_pk_bf16_f32 v37, v38, v39
	v_cvt_pk_bf16_f32 v38, v40, v41
	v_cvt_pk_bf16_f32 v39, v42, v43
	v_cvt_pk_bf16_f32 v44, v44, v45
	v_cvt_pk_bf16_f32 v45, v46, v47
	v_cvt_pk_bf16_f32 v46, v48, v49
	v_cvt_pk_bf16_f32 v47, v50, v51
	v_cvt_pk_bf16_f32 v52, v52, v53
	v_cvt_pk_bf16_f32 v53, v54, v55
	v_cvt_pk_bf16_f32 v54, v56, v57
	v_cvt_pk_bf16_f32 v55, v58, v59
	v_cvt_pk_bf16_f32 v60, v60, v61
	v_cvt_pk_bf16_f32 v61, v62, v63
	v_cvt_pk_bf16_f32 v62, v64, v65
	v_cvt_pk_bf16_f32 v63, v66, v67
	global_store_dwordx4 v8, v[36:39], s[34:35]
	global_store_dwordx4 v9, v[44:47], s[34:35]
	global_store_dwordx4 v10, v[52:55], s[34:35]
	global_store_dwordx4 v11, v[60:63], s[34:35]
	s_cmp_ge_u32 s20, s19
	s_mov_b32 s42, 0
	s_cbranch_scc1 .Ltrp0_skipA
	s_mov_b32 s26, s20
	s_cmp_lt_u32 s26, 0x2080
	s_cbranch_scc1 .Ltrp0_i4_s0
	s_sub_u32 s26, s26, 0x2080
	s_cmp_lt_u32 s26, 0x400
	s_cbranch_scc1 .Ltrp0_i4_s1
	s_sub_u32 s26, s26, 0x400
	s_cmp_lt_u32 s26, 0x100
	s_cbranch_scc1 .Ltrp0_i4_s2
	s_sub_u32 s26, s26, 0x100
	s_branch .Ltrp0_i4_s3

.Ltrp0_p5_ng:
	v_cvt_pk_bf16_f32 v36, v36, v37
	v_cvt_pk_bf16_f32 v37, v38, v39
	v_cvt_pk_bf16_f32 v38, v40, v41
	v_cvt_pk_bf16_f32 v39, v42, v43
	v_cvt_pk_bf16_f32 v44, v44, v45
	v_cvt_pk_bf16_f32 v45, v46, v47
	v_cvt_pk_bf16_f32 v46, v48, v49
	v_cvt_pk_bf16_f32 v47, v50, v51
	v_cvt_pk_bf16_f32 v52, v52, v53
	v_cvt_pk_bf16_f32 v53, v54, v55
	v_cvt_pk_bf16_f32 v54, v56, v57
	v_cvt_pk_bf16_f32 v55, v58, v59
	v_cvt_pk_bf16_f32 v60, v60, v61
	v_cvt_pk_bf16_f32 v61, v62, v63
	v_cvt_pk_bf16_f32 v62, v64, v65
	v_cvt_pk_bf16_f32 v63, v66, v67
	global_store_dwordx4 v8, v[36:39], s[38:39]
	global_store_dwordx4 v9, v[44:47], s[38:39]
	global_store_dwordx4 v10, v[52:55], s[38:39]
	global_store_dwordx4 v11, v[60:63], s[38:39]
	s_cmp_ge_u32 s20, s19
	s_mov_b32 s43, 0
	s_cbranch_scc1 .Ltrp0_skipB
	s_mov_b32 s26, s20
	s_cmp_lt_u32 s26, 0x2080
	s_cbranch_scc1 .Ltrp0_i6_s0
	s_sub_u32 s26, s26, 0x2080
	s_cmp_lt_u32 s26, 0x400
	s_cbranch_scc1 .Ltrp0_i6_s1
	s_sub_u32 s26, s26, 0x400
	s_cmp_lt_u32 s26, 0x100
	s_cbranch_scc1 .Ltrp0_i6_s2
	s_sub_u32 s26, s26, 0x100
	s_branch .Ltrp0_i6_s3

.LBB0_112:
	s_or_b64 exec, exec, s[4:5]
	s_cmp_eq_u32 s99, 0
	s_cbranch_scc1 .Lrc_p0b
	s_cmp_eq_u32 s99, 2
	s_cbranch_scc1 .Lrc_p0done
	s_cmp_eq_u32 s99, 3
	s_cbranch_scc1 .Lrc_c2
	s_cmp_eq_u32 s99, 7
	s_cbranch_scc1 .Lrc_p1ret
	s_cmp_eq_u32 s99, 9
	s_cbranch_scc1 .Lrc_p1ret
	s_cmp_eq_u32 s99, 4
	s_cbranch_scc0 .LBB0_113
	s_mov_b32 s2, s100
	s_mov_b32 s99, 6
	s_branch .LBB0_949

.LBB0_693:
	s_cmp_lt_u32 s2, 8
	s_barrier
	s_cbranch_scc1 .LBB0_950
	s_mov_b64 exec, -1
	v_readlane_b32 s0, v254, 0
	v_readlane_b32 s1, v254, 1
	s_nop 4
	s_load_dwordx2 s[56:57], s[0:1], 0xa8
	s_load_dwordx2 s[58:59], s[0:1], 0xc0
	s_load_dwordx2 s[60:61], s[0:1], 0x88
	s_load_dwordx2 s[62:63], s[0:1], 0x78
	s_load_dwordx2 s[64:65], s[0:1], 0x80
	s_load_dwordx2 s[66:67], s[0:1], 0x90
	s_load_dwordx2 s[68:69], s[0:1], 0xa0
	s_load_dwordx2 s[70:71], s[0:1], 0x48
	s_load_dwordx2 s[72:73], s[0:1], 0xd8
	s_load_dword s3, s[0:1], 0xe8
	v_readfirstlane_b32 s4, v0
	v_and_b32_e32 v7, 63, v0
	s_lshr_b32 s4, s4, 6
	v_lshrrev_b32_e32 v1, 3, v7
	v_and_b32_e32 v2, 7, v7
	s_lshl_b32 s5, s4, 14
	v_lshlrev_b32_e32 v5, 5, v2
	s_movk_i32 s14, 0x420
	v_mul_u32_u24_e32 v4, s14, v2
	v_lshlrev_b32_e32 v2, 4, v2
	s_movk_i32 s14, 0x84
	v_mad_u32_u24 v3, v1, s14, v2
	v_lshl_add_u32 v4, v1, 2, v4
	v_add_u32_e32 v3, s5, v3
	v_add_u32_e32 v4, s5, v4
	v_mov_b32_e32 v207, v3
	v_add_u32_e32 v208, 1056, v3
	v_add_u32_e32 v209, 2112, v3
	v_add_u32_e32 v210, 3168, v3
	v_add_u32_e32 v211, 4224, v3
	v_add_u32_e32 v212, 5280, v3
	v_add_u32_e32 v213, 6336, v3
	v_add_u32_e32 v214, 7392, v3
	s_waitcnt lgkmcnt(0)
	s_sub_u32 s5, s2, 8
	s_lshl_b32 s5, s5, 3
	s_add_u32 s20, s5, s4
	s_sub_u32 s21, s3, 8
	s_lshl_b32 s21, s21, 3
	s_mov_b32 s19, 0x5600
	s_cmp_ge_u32 s20, s19
	s_cbranch_scc1 .Lrc_p3call
	s_mov_b32 s42, 0
	s_mov_b32 s43, 0
	s_mov_b32 s26, s20
	s_cmp_lt_u32 s26, 0x2c00
	s_cbranch_scc1 .Ltrp3_i1_s0
	s_sub_u32 s26, s26, 0x2c00
	s_cmp_lt_u32 s26, 0x1600
	s_cbranch_scc1 .Ltrp3_i1_s1
	s_sub_u32 s26, s26, 0x1600
	s_cmp_lt_u32 s26, 0x800
	s_cbranch_scc1 .Ltrp3_i1_s2
	s_sub_u32 s26, s26, 0x800
	s_cmp_lt_u32 s26, 0x400
	s_cbranch_scc1 .Ltrp3_i1_s3
	s_sub_u32 s26, s26, 0x400
	s_cmp_lt_u32 s26, 0x400
	s_cbranch_scc1 .Ltrp3_i1_s4
	s_sub_u32 s26, s26, 0x400
	s_cmp_lt_u32 s26, 0x200
	s_cbranch_scc1 .Ltrp3_i1_s5
	s_sub_u32 s26, s26, 0x200
	s_branch .Ltrp3_i1_s6

.Ltrp3_i1_c:
	s_lshl_b32 s4, s24, 6
	s_mul_i32 s4, s25, s4
	s_lshl_b32 s5, s27, 7
	s_add_u32 s4, s4, s5
	s_add_u32 s10, s22, s4
	s_addc_u32 s11, s23, 0
	v_mad_u32_u24 v6, v1, s24, v2
	s_lshl_b32 s4, s29, 5
	s_mul_i32 s4, s27, s4
	s_lshl_b32 s5, s25, 7
	s_add_u32 s4, s4, s5
	s_add_u32 s4, s4, s28
	s_add_u32 s74, s72, s4
	s_addc_u32 s75, s73, 0
	s_mov_b32 s76, s29
	s_mov_b32 s77, s31
	s_lshl_b32 s4, s25, 8
	s_add_u32 s4, s4, s30
	s_add_u32 s12, s70, s4
	s_addc_u32 s13, s71, 0
	s_lshl_b32 s14, s24, 3
	global_load_dwordx4 v[44:47], v6, s[10:11]
	s_add_u32 s10, s10, s14
	s_addc_u32 s11, s11, 0
	global_load_dwordx4 v[48:51], v6, s[10:11]
	s_add_u32 s10, s10, s14
	s_addc_u32 s11, s11, 0
	global_load_dwordx4 v[52:55], v6, s[10:11]
	s_add_u32 s10, s10, s14
	s_addc_u32 s11, s11, 0
	global_load_dwordx4 v[56:59], v6, s[10:11]
	s_add_u32 s10, s10, s14
	s_addc_u32 s11, s11, 0
	global_load_dwordx4 v[60:63], v6, s[10:11]
	s_add_u32 s10, s10, s14
	s_addc_u32 s11, s11, 0
	global_load_dwordx4 v[64:67], v6, s[10:11]
	s_add_u32 s10, s10, s14
	s_addc_u32 s11, s11, 0
	global_load_dwordx4 v[68:71], v6, s[10:11]
	s_add_u32 s10, s10, s14
	s_addc_u32 s11, s11, 0
	global_load_dwordx4 v[72:75], v6, s[10:11]
	global_load_dwordx4 v[76:79], v5, s[12:13]
	global_load_dwordx4 v[80:83], v5, s[12:13] offset:16
	s_add_u32 s20, s20, s21
	s_add_u32 s42, s42, 1
	s_cmp_ge_u32 s20, s19
	s_cbranch_scc1 .Ltrp3_st0
	s_mov_b32 s26, s20
	s_cmp_lt_u32 s26, 0x2c00
	s_cbranch_scc1 .Ltrp3_i2_s0
	s_sub_u32 s26, s26, 0x2c00
	s_cmp_lt_u32 s26, 0x1600
	s_cbranch_scc1 .Ltrp3_i2_s1
	s_sub_u32 s26, s26, 0x1600
	s_cmp_lt_u32 s26, 0x800
	s_cbranch_scc1 .Ltrp3_i2_s2
	s_sub_u32 s26, s26, 0x800
	s_cmp_lt_u32 s26, 0x400
	s_cbranch_scc1 .Ltrp3_i2_s3
	s_sub_u32 s26, s26, 0x400
	s_cmp_lt_u32 s26, 0x400
	s_cbranch_scc1 .Ltrp3_i2_s4
	s_sub_u32 s26, s26, 0x400
	s_cmp_lt_u32 s26, 0x200
	s_cbranch_scc1 .Ltrp3_i2_s5
	s_sub_u32 s26, s26, 0x200
	s_branch .Ltrp3_i2_s6

.Ltrp3_i2_c:
	s_lshl_b32 s4, s24, 6
	s_mul_i32 s4, s25, s4
	s_lshl_b32 s5, s27, 7
	s_add_u32 s4, s4, s5
	s_add_u32 s10, s22, s4
	s_addc_u32 s11, s23, 0
	v_mad_u32_u24 v6, v1, s24, v2
	s_lshl_b32 s4, s29, 5
	s_mul_i32 s4, s27, s4
	s_lshl_b32 s5, s25, 7
	s_add_u32 s4, s4, s5
	s_add_u32 s4, s4, s28
	s_add_u32 s78, s72, s4
	s_addc_u32 s79, s73, 0
	s_mov_b32 s80, s29
	s_mov_b32 s81, s31
	s_lshl_b32 s4, s25, 8
	s_add_u32 s4, s4, s30
	s_add_u32 s12, s70, s4
	s_addc_u32 s13, s71, 0
	s_lshl_b32 s14, s24, 3
	global_load_dwordx4 v[84:87], v6, s[10:11]
	s_add_u32 s10, s10, s14
	s_addc_u32 s11, s11, 0
	global_load_dwordx4 v[88:91], v6, s[10:11]
	s_add_u32 s10, s10, s14
	s_addc_u32 s11, s11, 0
	global_load_dwordx4 v[92:95], v6, s[10:11]
	s_add_u32 s10, s10, s14
	s_addc_u32 s11, s11, 0
	global_load_dwordx4 v[96:99], v6, s[10:11]
	s_add_u32 s10, s10, s14
	s_addc_u32 s11, s11, 0
	global_load_dwordx4 v[100:103], v6, s[10:11]
	s_add_u32 s10, s10, s14
	s_addc_u32 s11, s11, 0
	global_load_dwordx4 v[104:107], v6, s[10:11]
	s_add_u32 s10, s10, s14
	s_addc_u32 s11, s11, 0
	global_load_dwordx4 v[108:111], v6, s[10:11]
	s_add_u32 s10, s10, s14
	s_addc_u32 s11, s11, 0
	global_load_dwordx4 v[112:115], v6, s[10:11]
	global_load_dwordx4 v[116:119], v5, s[12:13]
	global_load_dwordx4 v[120:123], v5, s[12:13] offset:16
	s_add_u32 s20, s20, s21
	s_add_u32 s42, s42, 1
	s_cmp_ge_u32 s20, s19
	s_cbranch_scc1 .Ltrp3_st0
	s_mov_b32 s26, s20
	s_cmp_lt_u32 s26, 0x2c00
	s_cbranch_scc1 .Ltrp3_i3_s0
	s_sub_u32 s26, s26, 0x2c00
	s_cmp_lt_u32 s26, 0x1600
	s_cbranch_scc1 .Ltrp3_i3_s1
	s_sub_u32 s26, s26, 0x1600
	s_cmp_lt_u32 s26, 0x800
	s_cbranch_scc1 .Ltrp3_i3_s2
	s_sub_u32 s26, s26, 0x800
	s_cmp_lt_u32 s26, 0x400
	s_cbranch_scc1 .Ltrp3_i3_s3
	s_sub_u32 s26, s26, 0x400
	s_cmp_lt_u32 s26, 0x400
	s_cbranch_scc1 .Ltrp3_i3_s4
	s_sub_u32 s26, s26, 0x400
	s_cmp_lt_u32 s26, 0x200
	s_cbranch_scc1 .Ltrp3_i3_s5
	s_sub_u32 s26, s26, 0x200
	s_branch .Ltrp3_i3_s6

.Ltrp3_i3_c:
	s_lshl_b32 s4, s24, 6
	s_mul_i32 s4, s25, s4
	s_lshl_b32 s5, s27, 7
	s_add_u32 s4, s4, s5
	s_add_u32 s10, s22, s4
	s_addc_u32 s11, s23, 0
	v_mad_u32_u24 v6, v1, s24, v2
	s_lshl_b32 s4, s29, 5
	s_mul_i32 s4, s27, s4
	s_lshl_b32 s5, s25, 7
	s_add_u32 s4, s4, s5
	s_add_u32 s4, s4, s28
	s_add_u32 s82, s72, s4
	s_addc_u32 s83, s73, 0
	s_mov_b32 s84, s29
	s_mov_b32 s85, s31
	s_lshl_b32 s4, s25, 8
	s_add_u32 s4, s4, s30
	s_add_u32 s12, s70, s4
	s_addc_u32 s13, s71, 0
	s_lshl_b32 s14, s24, 3
	global_load_dwordx4 v[124:127], v6, s[10:11]
	s_add_u32 s10, s10, s14
	s_addc_u32 s11, s11, 0
	global_load_dwordx4 v[128:131], v6, s[10:11]
	s_add_u32 s10, s10, s14
	s_addc_u32 s11, s11, 0
	global_load_dwordx4 v[132:135], v6, s[10:11]
	s_add_u32 s10, s10, s14
	s_addc_u32 s11, s11, 0
	global_load_dwordx4 v[136:139], v6, s[10:11]
	s_add_u32 s10, s10, s14
	s_addc_u32 s11, s11, 0
	global_load_dwordx4 v[140:143], v6, s[10:11]
	s_add_u32 s10, s10, s14
	s_addc_u32 s11, s11, 0
	global_load_dwordx4 v[144:147], v6, s[10:11]
	s_add_u32 s10, s10, s14
	s_addc_u32 s11, s11, 0
	global_load_dwordx4 v[148:151], v6, s[10:11]
	s_add_u32 s10, s10, s14
	s_addc_u32 s11, s11, 0
	global_load_dwordx4 v[152:155], v6, s[10:11]
	global_load_dwordx4 v[156:159], v5, s[12:13]
	global_load_dwordx4 v[160:163], v5, s[12:13] offset:16
	s_add_u32 s20, s20, s21
	s_add_u32 s42, s42, 1
	s_cmp_ge_u32 s20, s19
	s_cbranch_scc1 .Ltrp3_st0
	s_mov_b32 s26, s20
	s_cmp_lt_u32 s26, 0x2c00
	s_cbranch_scc1 .Ltrp3_i4_s0
	s_sub_u32 s26, s26, 0x2c00
	s_cmp_lt_u32 s26, 0x1600
	s_cbranch_scc1 .Ltrp3_i4_s1
	s_sub_u32 s26, s26, 0x1600
	s_cmp_lt_u32 s26, 0x800
	s_cbranch_scc1 .Ltrp3_i4_s2
	s_sub_u32 s26, s26, 0x800
	s_cmp_lt_u32 s26, 0x400
	s_cbranch_scc1 .Ltrp3_i4_s3
	s_sub_u32 s26, s26, 0x400
	s_cmp_lt_u32 s26, 0x400
	s_cbranch_scc1 .Ltrp3_i4_s4
	s_sub_u32 s26, s26, 0x400
	s_cmp_lt_u32 s26, 0x200
	s_cbranch_scc1 .Ltrp3_i4_s5
	s_sub_u32 s26, s26, 0x200
	s_branch .Ltrp3_i4_s6

.Ltrp3_p5_ng:
	v_cvt_pk_bf16_f32 v12, v12, v13
	v_cvt_pk_bf16_f32 v13, v14, v15
	v_cvt_pk_bf16_f32 v14, v16, v17
	v_cvt_pk_bf16_f32 v15, v18, v19
	v_cvt_pk_bf16_f32 v20, v20, v21
	v_cvt_pk_bf16_f32 v21, v22, v23
	v_cvt_pk_bf16_f32 v22, v24, v25
	v_cvt_pk_bf16_f32 v23, v26, v27
	v_cvt_pk_bf16_f32 v28, v28, v29
	v_cvt_pk_bf16_f32 v29, v30, v31
	v_cvt_pk_bf16_f32 v30, v32, v33
	v_cvt_pk_bf16_f32 v31, v34, v35
	v_cvt_pk_bf16_f32 v36, v36, v37
	v_cvt_pk_bf16_f32 v37, v38, v39
	v_cvt_pk_bf16_f32 v38, v40, v41
	v_cvt_pk_bf16_f32 v39, v42, v43
	global_store_dwordx4 v8, v[12:15], s[74:75]
	global_store_dwordx4 v9, v[20:23], s[74:75]
	global_store_dwordx4 v10, v[28:31], s[74:75]
	global_store_dwordx4 v11, v[36:39], s[74:75]
	s_sub_u32 s42, s42, 1
	s_add_u32 s43, s43, 1
	s_cmp_ge_u32 s20, s19
	s_cbranch_scc1 .Ltrp3_ni_0
	s_mov_b32 s26, s20
	s_cmp_lt_u32 s26, 0x2c00
	s_cbranch_scc1 .Ltrp3_i6_s0
	s_sub_u32 s26, s26, 0x2c00
	s_cmp_lt_u32 s26, 0x1600
	s_cbranch_scc1 .Ltrp3_i6_s1
	s_sub_u32 s26, s26, 0x1600
	s_cmp_lt_u32 s26, 0x800
	s_cbranch_scc1 .Ltrp3_i6_s2
	s_sub_u32 s26, s26, 0x800
	s_cmp_lt_u32 s26, 0x400
	s_cbranch_scc1 .Ltrp3_i6_s3
	s_sub_u32 s26, s26, 0x400
	s_cmp_lt_u32 s26, 0x400
	s_cbranch_scc1 .Ltrp3_i6_s4
	s_sub_u32 s26, s26, 0x400
	s_cmp_lt_u32 s26, 0x200
	s_cbranch_scc1 .Ltrp3_i6_s5
	s_sub_u32 s26, s26, 0x200
	s_branch .Ltrp3_i6_s6

.Ltrp3_p7_ng:
	v_cvt_pk_bf16_f32 v12, v12, v13
	v_cvt_pk_bf16_f32 v13, v14, v15
	v_cvt_pk_bf16_f32 v14, v16, v17
	v_cvt_pk_bf16_f32 v15, v18, v19
	v_cvt_pk_bf16_f32 v20, v20, v21
	v_cvt_pk_bf16_f32 v21, v22, v23
	v_cvt_pk_bf16_f32 v22, v24, v25
	v_cvt_pk_bf16_f32 v23, v26, v27
	v_cvt_pk_bf16_f32 v28, v28, v29
	v_cvt_pk_bf16_f32 v29, v30, v31
	v_cvt_pk_bf16_f32 v30, v32, v33
	v_cvt_pk_bf16_f32 v31, v34, v35
	v_cvt_pk_bf16_f32 v36, v36, v37
	v_cvt_pk_bf16_f32 v37, v38, v39
	v_cvt_pk_bf16_f32 v38, v40, v41
	v_cvt_pk_bf16_f32 v39, v42, v43
	global_store_dwordx4 v8, v[12:15], s[78:79]
	global_store_dwordx4 v9, v[20:23], s[78:79]
	global_store_dwordx4 v10, v[28:31], s[78:79]
	global_store_dwordx4 v11, v[36:39], s[78:79]
	s_sub_u32 s42, s42, 1
	s_add_u32 s43, s43, 1
	s_cmp_ge_u32 s20, s19
	s_cbranch_scc1 .Ltrp3_ni_1
	s_mov_b32 s26, s20
	s_cmp_lt_u32 s26, 0x2c00
	s_cbranch_scc1 .Ltrp3_i8_s0
	s_sub_u32 s26, s26, 0x2c00
	s_cmp_lt_u32 s26, 0x1600
	s_cbranch_scc1 .Ltrp3_i8_s1
	s_sub_u32 s26, s26, 0x1600
	s_cmp_lt_u32 s26, 0x800
	s_cbranch_scc1 .Ltrp3_i8_s2
	s_sub_u32 s26, s26, 0x800
	s_cmp_lt_u32 s26, 0x400
	s_cbranch_scc1 .Ltrp3_i8_s3
	s_sub_u32 s26, s26, 0x400
	s_cmp_lt_u32 s26, 0x400
	s_cbranch_scc1 .Ltrp3_i8_s4
	s_sub_u32 s26, s26, 0x400
	s_cmp_lt_u32 s26, 0x200
	s_cbranch_scc1 .Ltrp3_i8_s5
	s_sub_u32 s26, s26, 0x200
	s_branch .Ltrp3_i8_s6

.Ltrp3_p9_ng:
	v_cvt_pk_bf16_f32 v12, v12, v13
	v_cvt_pk_bf16_f32 v13, v14, v15
	v_cvt_pk_bf16_f32 v14, v16, v17
	v_cvt_pk_bf16_f32 v15, v18, v19
	v_cvt_pk_bf16_f32 v20, v20, v21
	v_cvt_pk_bf16_f32 v21, v22, v23
	v_cvt_pk_bf16_f32 v22, v24, v25
	v_cvt_pk_bf16_f32 v23, v26, v27
	v_cvt_pk_bf16_f32 v28, v28, v29
	v_cvt_pk_bf16_f32 v29, v30, v31
	v_cvt_pk_bf16_f32 v30, v32, v33
	v_cvt_pk_bf16_f32 v31, v34, v35
	v_cvt_pk_bf16_f32 v36, v36, v37
	v_cvt_pk_bf16_f32 v37, v38, v39
	v_cvt_pk_bf16_f32 v38, v40, v41
	v_cvt_pk_bf16_f32 v39, v42, v43
	global_store_dwordx4 v8, v[12:15], s[82:83]
	global_store_dwordx4 v9, v[20:23], s[82:83]
	global_store_dwordx4 v10, v[28:31], s[82:83]
	global_store_dwordx4 v11, v[36:39], s[82:83]
	s_sub_u32 s42, s42, 1
	s_add_u32 s43, s43, 1
	s_cmp_ge_u32 s20, s19
	s_cbranch_scc1 .Ltrp3_ni_2
	s_mov_b32 s26, s20
	s_cmp_lt_u32 s26, 0x2c00
	s_cbranch_scc1 .Ltrp3_i10_s0
	s_sub_u32 s26, s26, 0x2c00
	s_cmp_lt_u32 s26, 0x1600
	s_cbranch_scc1 .Ltrp3_i10_s1
	s_sub_u32 s26, s26, 0x1600
	s_cmp_lt_u32 s26, 0x800
	s_cbranch_scc1 .Ltrp3_i10_s2
	s_sub_u32 s26, s26, 0x800
	s_cmp_lt_u32 s26, 0x400
	s_cbranch_scc1 .Ltrp3_i10_s3
	s_sub_u32 s26, s26, 0x400
	s_cmp_lt_u32 s26, 0x400
	s_cbranch_scc1 .Ltrp3_i10_s4
	s_sub_u32 s26, s26, 0x400
	s_cmp_lt_u32 s26, 0x200
	s_cbranch_scc1 .Ltrp3_i10_s5
	s_sub_u32 s26, s26, 0x200
	s_branch .Ltrp3_i10_s6

.Ltrp3_p11_ng:
	v_cvt_pk_bf16_f32 v12, v12, v13
	v_cvt_pk_bf16_f32 v13, v14, v15
	v_cvt_pk_bf16_f32 v14, v16, v17
	v_cvt_pk_bf16_f32 v15, v18, v19
	v_cvt_pk_bf16_f32 v20, v20, v21
	v_cvt_pk_bf16_f32 v21, v22, v23
	v_cvt_pk_bf16_f32 v22, v24, v25
	v_cvt_pk_bf16_f32 v23, v26, v27
	v_cvt_pk_bf16_f32 v28, v28, v29
	v_cvt_pk_bf16_f32 v29, v30, v31
	v_cvt_pk_bf16_f32 v30, v32, v33
	v_cvt_pk_bf16_f32 v31, v34, v35
	v_cvt_pk_bf16_f32 v36, v36, v37
	v_cvt_pk_bf16_f32 v37, v38, v39
	v_cvt_pk_bf16_f32 v38, v40, v41
	v_cvt_pk_bf16_f32 v39, v42, v43
	global_store_dwordx4 v8, v[12:15], s[86:87]
	global_store_dwordx4 v9, v[20:23], s[86:87]
	global_store_dwordx4 v10, v[28:31], s[86:87]
	global_store_dwordx4 v11, v[36:39], s[86:87]
	s_sub_u32 s42, s42, 1
	s_add_u32 s43, s43, 1
	s_cmp_ge_u32 s20, s19
	s_cbranch_scc1 .Ltrp3_ni_3
	s_mov_b32 s26, s20
	s_cmp_lt_u32 s26, 0x2c00
	s_cbranch_scc1 .Ltrp3_i12_s0
	s_sub_u32 s26, s26, 0x2c00
	s_cmp_lt_u32 s26, 0x1600
	s_cbranch_scc1 .Ltrp3_i12_s1
	s_sub_u32 s26, s26, 0x1600
	s_cmp_lt_u32 s26, 0x800
	s_cbranch_scc1 .Ltrp3_i12_s2
	s_sub_u32 s26, s26, 0x800
	s_cmp_lt_u32 s26, 0x400
	s_cbranch_scc1 .Ltrp3_i12_s3
	s_sub_u32 s26, s26, 0x400
	s_cmp_lt_u32 s26, 0x400
	s_cbranch_scc1 .Ltrp3_i12_s4
	s_sub_u32 s26, s26, 0x400
	s_cmp_lt_u32 s26, 0x200
	s_cbranch_scc1 .Ltrp3_i12_s5
	s_sub_u32 s26, s26, 0x200
	s_branch .Ltrp3_i12_s6

.LBB0_2705:
	v_lshl_add_u32 v144, s26, 8, v1
	v_ashrrev_i32_e32 v145, 31, v144
	s_nop 15
	s_nop 15
	v_bfe_u32 v234, v206, 4, 1
	v_mul_u32_u24_e32 v234, 24, v234
	v_mov_b32_e32 v235, 0
	v_lshl_add_u64 v[152:153], v[144:145], 2, s[12:13]
	global_load_dword v154, v[152:153], off
	s_lshl_b32 s0, s27, 8
	v_mov_b64_e32 v[146:147], s[10:11]
	s_ashr_i32 s1, s0, 31
	v_mad_i64_i32 v[156:157], s[26:27], v144, s52, v[146:147]
	s_lshl_b64 s[26:27], s[0:1], 1
	s_nop 0
	v_lshl_add_u64 v[156:157], v[156:157], 0, s[26:27]
	v_lshl_add_u64 v[156:157], v[156:157], 0, v[134:135]
	s_andn2_b64 vcc, exec, s[4:5]
	s_mov_b64 s[4:5], -1
	s_waitcnt vmcnt(0)
	v_pk_mul_f32 v[126:127], v[126:127], v[154:155] op_sel_hi:[1,0]
	v_pk_mul_f32 v[128:129], v[128:129], v[154:155] op_sel_hi:[1,0]
	v_cvt_pk_bf16_f32 v224, v126, v127
	s_nop 0
	v_cvt_pk_bf16_f32 v225, v128, v129
	s_nop 0
	global_load_dword v126, v[152:153], off
	s_waitcnt vmcnt(0)
	v_pk_mul_f32 v[122:123], v[122:123], v[126:127] op_sel_hi:[1,0]
	v_pk_mul_f32 v[124:125], v[124:125], v[126:127] op_sel_hi:[1,0]
	v_cvt_pk_bf16_f32 v226, v122, v123
	s_nop 0
	v_cvt_pk_bf16_f32 v227, v124, v125
	s_nop 1
	v_permlane16_swap_b32_e32 v224, v226
	v_permlane16_swap_b32_e32 v225, v227
	v_lshl_add_u64 v[232:233], v[156:157], 0, v[234:235]
	global_store_dwordx4 v[232:233], v[224:227], off
	global_load_dword v122, v[152:153], off
	s_waitcnt vmcnt(0)
	v_pk_mul_f32 v[118:119], v[118:119], v[122:123] op_sel_hi:[1,0]
	v_pk_mul_f32 v[120:121], v[120:121], v[122:123] op_sel_hi:[1,0]
	v_cvt_pk_bf16_f32 v228, v118, v119
	s_nop 0
	v_cvt_pk_bf16_f32 v229, v120, v121
	s_nop 0
	global_load_dword v118, v[152:153], off
	v_or_b32_e32 v120, 16, v144
	v_ashrrev_i32_e32 v121, 31, v120
	v_lshl_add_u64 v[122:123], v[120:121], 2, s[12:13]
	s_waitcnt vmcnt(0)
	v_pk_mul_f32 v[110:111], v[110:111], v[118:119] op_sel_hi:[1,0]
	v_pk_mul_f32 v[112:113], v[112:113], v[118:119] op_sel_hi:[1,0]
	v_cvt_pk_bf16_f32 v230, v110, v111
	s_nop 0
	v_cvt_pk_bf16_f32 v231, v112, v113
	s_nop 1
	v_permlane16_swap_b32_e32 v228, v230
	v_permlane16_swap_b32_e32 v229, v231
	v_lshl_add_u64 v[232:233], v[156:157], 0, v[234:235]
	global_store_dwordx4 v[232:233], v[228:231], off offset:256
	global_load_dword v110, v[122:123], off
	v_mad_i64_i32 v[112:113], s[0:1], v120, s52, v[146:147]
	v_lshl_add_u64 v[112:113], v[112:113], 0, s[26:27]
	v_lshl_add_u64 v[112:113], v[112:113], 0, v[134:135]
	s_waitcnt vmcnt(0)
	v_pk_mul_f32 v[116:117], v[116:117], v[110:111] op_sel_hi:[1,0]
	v_pk_mul_f32 v[110:111], v[114:115], v[110:111] op_sel_hi:[1,0]
	s_nop 0
	v_cvt_pk_bf16_f32 v224, v110, v111
	v_cvt_pk_bf16_f32 v225, v116, v117
	s_nop 0
	global_load_dword v110, v[122:123], off
	s_waitcnt vmcnt(0)
	v_pk_mul_f32 v[106:107], v[106:107], v[110:111] op_sel_hi:[1,0]
	v_pk_mul_f32 v[108:109], v[108:109], v[110:111] op_sel_hi:[1,0]
	v_cvt_pk_bf16_f32 v226, v106, v107
	s_nop 0
	v_cvt_pk_bf16_f32 v227, v108, v109
	s_nop 1
	v_permlane16_swap_b32_e32 v224, v226
	v_permlane16_swap_b32_e32 v225, v227
	v_lshl_add_u64 v[232:233], v[112:113], 0, v[234:235]
	global_store_dwordx4 v[232:233], v[224:227], off
	global_load_dword v106, v[122:123], off
	s_waitcnt vmcnt(0)
	v_pk_mul_f32 v[102:103], v[102:103], v[106:107] op_sel_hi:[1,0]
	v_pk_mul_f32 v[104:105], v[104:105], v[106:107] op_sel_hi:[1,0]
	v_cvt_pk_bf16_f32 v228, v102, v103
	s_nop 0
	v_cvt_pk_bf16_f32 v229, v104, v105
	s_nop 0
	global_load_dword v102, v[122:123], off
	v_or_b32_e32 v104, 32, v144
	v_ashrrev_i32_e32 v105, 31, v104
	v_lshl_add_u64 v[106:107], v[104:105], 2, s[12:13]
	s_waitcnt vmcnt(0)
	v_pk_mul_f32 v[94:95], v[94:95], v[102:103] op_sel_hi:[1,0]
	v_pk_mul_f32 v[96:97], v[96:97], v[102:103] op_sel_hi:[1,0]
	v_cvt_pk_bf16_f32 v230, v94, v95
	s_nop 0
	v_cvt_pk_bf16_f32 v231, v96, v97
	s_nop 1
	v_permlane16_swap_b32_e32 v228, v230
	v_permlane16_swap_b32_e32 v229, v231
	v_lshl_add_u64 v[232:233], v[112:113], 0, v[234:235]
	global_store_dwordx4 v[232:233], v[228:231], off offset:256
	global_load_dword v94, v[106:107], off
	v_mad_i64_i32 v[96:97], s[0:1], v104, s52, v[146:147]
	v_lshl_add_u64 v[96:97], v[96:97], 0, s[26:27]
	v_lshl_add_u64 v[96:97], v[96:97], 0, v[134:135]
	s_waitcnt vmcnt(0)
	v_pk_mul_f32 v[100:101], v[100:101], v[94:95] op_sel_hi:[1,0]
	v_pk_mul_f32 v[94:95], v[98:99], v[94:95] op_sel_hi:[1,0]
	s_nop 0
	v_cvt_pk_bf16_f32 v224, v94, v95
	v_cvt_pk_bf16_f32 v225, v100, v101
	s_nop 0
	global_load_dword v94, v[106:107], off
	s_waitcnt vmcnt(0)
	v_pk_mul_f32 v[90:91], v[90:91], v[94:95] op_sel_hi:[1,0]
	v_pk_mul_f32 v[92:93], v[92:93], v[94:95] op_sel_hi:[1,0]
	v_cvt_pk_bf16_f32 v226, v90, v91
	s_nop 0
	v_cvt_pk_bf16_f32 v227, v92, v93
	s_nop 1
	v_permlane16_swap_b32_e32 v224, v226
	v_permlane16_swap_b32_e32 v225, v227
	v_lshl_add_u64 v[232:233], v[96:97], 0, v[234:235]
	global_store_dwordx4 v[232:233], v[224:227], off
	global_load_dword v90, v[106:107], off
	s_waitcnt vmcnt(0)
	v_pk_mul_f32 v[86:87], v[86:87], v[90:91] op_sel_hi:[1,0]
	v_pk_mul_f32 v[88:89], v[88:89], v[90:91] op_sel_hi:[1,0]
	v_cvt_pk_bf16_f32 v228, v86, v87
	s_nop 0
	v_cvt_pk_bf16_f32 v229, v88, v89
	s_nop 0
	global_load_dword v86, v[106:107], off
	v_or_b32_e32 v88, 48, v144
	v_ashrrev_i32_e32 v89, 31, v88
	v_lshl_add_u64 v[90:91], v[88:89], 2, s[12:13]
	s_waitcnt vmcnt(0)
	v_pk_mul_f32 v[78:79], v[78:79], v[86:87] op_sel_hi:[1,0]
	v_pk_mul_f32 v[80:81], v[80:81], v[86:87] op_sel_hi:[1,0]
	v_cvt_pk_bf16_f32 v230, v78, v79
	s_nop 0
	v_cvt_pk_bf16_f32 v231, v80, v81
	s_nop 1
	v_permlane16_swap_b32_e32 v228, v230
	v_permlane16_swap_b32_e32 v229, v231
	v_lshl_add_u64 v[232:233], v[96:97], 0, v[234:235]
	global_store_dwordx4 v[232:233], v[228:231], off offset:256
	global_load_dword v78, v[90:91], off
	v_mad_i64_i32 v[80:81], s[0:1], v88, s52, v[146:147]
	v_lshl_add_u64 v[80:81], v[80:81], 0, s[26:27]
	v_lshl_add_u64 v[80:81], v[80:81], 0, v[134:135]
	s_waitcnt vmcnt(0)
	v_pk_mul_f32 v[84:85], v[84:85], v[78:79] op_sel_hi:[1,0]
	v_pk_mul_f32 v[78:79], v[82:83], v[78:79] op_sel_hi:[1,0]
	s_nop 0
	v_cvt_pk_bf16_f32 v224, v78, v79
	v_cvt_pk_bf16_f32 v225, v84, v85
	s_nop 0
	global_load_dword v78, v[90:91], off
	s_waitcnt vmcnt(0)
	v_pk_mul_f32 v[74:75], v[74:75], v[78:79] op_sel_hi:[1,0]
	v_pk_mul_f32 v[76:77], v[76:77], v[78:79] op_sel_hi:[1,0]
	v_cvt_pk_bf16_f32 v226, v74, v75
	s_nop 0
	v_cvt_pk_bf16_f32 v227, v76, v77
	s_nop 1
	v_permlane16_swap_b32_e32 v224, v226
	v_permlane16_swap_b32_e32 v225, v227
	v_lshl_add_u64 v[232:233], v[80:81], 0, v[234:235]
	global_store_dwordx4 v[232:233], v[224:227], off
	global_load_dword v74, v[90:91], off
	s_waitcnt vmcnt(0)
	v_pk_mul_f32 v[70:71], v[70:71], v[74:75] op_sel_hi:[1,0]
	v_pk_mul_f32 v[72:73], v[72:73], v[74:75] op_sel_hi:[1,0]
	v_cvt_pk_bf16_f32 v228, v70, v71
	s_nop 0
	v_cvt_pk_bf16_f32 v229, v72, v73
	s_nop 0
	global_load_dword v70, v[90:91], off
	v_add_u32_e32 v72, 0x80, v144
	v_ashrrev_i32_e32 v73, 31, v72
	v_lshl_add_u64 v[74:75], v[72:73], 2, s[12:13]
	s_waitcnt vmcnt(0)
	v_pk_mul_f32 v[66:67], v[66:67], v[70:71] op_sel_hi:[1,0]
	v_pk_mul_f32 v[68:69], v[68:69], v[70:71] op_sel_hi:[1,0]
	v_cvt_pk_bf16_f32 v230, v66, v67
	s_nop 0
	v_cvt_pk_bf16_f32 v231, v68, v69
	s_nop 1
	v_permlane16_swap_b32_e32 v228, v230
	v_permlane16_swap_b32_e32 v229, v231
	v_lshl_add_u64 v[232:233], v[80:81], 0, v[234:235]
	global_store_dwordx4 v[232:233], v[228:231], off offset:256
	global_load_dword v66, v[74:75], off
	v_mad_i64_i32 v[68:69], s[0:1], v72, s52, v[146:147]
	v_lshl_add_u64 v[68:69], v[68:69], 0, s[26:27]
	v_lshl_add_u64 v[68:69], v[68:69], 0, v[134:135]
	s_waitcnt vmcnt(0)
	v_pk_mul_f32 v[62:63], v[62:63], v[66:67] op_sel_hi:[1,0]
	v_pk_mul_f32 v[64:65], v[64:65], v[66:67] op_sel_hi:[1,0]
	v_cvt_pk_bf16_f32 v224, v62, v63
	s_nop 0
	v_cvt_pk_bf16_f32 v225, v64, v65
	s_nop 0
	global_load_dword v62, v[74:75], off
	s_waitcnt vmcnt(0)
	v_pk_mul_f32 v[58:59], v[58:59], v[62:63] op_sel_hi:[1,0]
	v_pk_mul_f32 v[60:61], v[60:61], v[62:63] op_sel_hi:[1,0]
	v_cvt_pk_bf16_f32 v226, v58, v59
	s_nop 0
	v_cvt_pk_bf16_f32 v227, v60, v61
	s_nop 1
	v_permlane16_swap_b32_e32 v224, v226
	v_permlane16_swap_b32_e32 v225, v227
	v_lshl_add_u64 v[232:233], v[68:69], 0, v[234:235]
	global_store_dwordx4 v[232:233], v[224:227], off
	global_load_dword v58, v[74:75], off
	s_waitcnt vmcnt(0)
	v_pk_mul_f32 v[54:55], v[54:55], v[58:59] op_sel_hi:[1,0]
	v_pk_mul_f32 v[56:57], v[56:57], v[58:59] op_sel_hi:[1,0]
	v_cvt_pk_bf16_f32 v228, v54, v55
	s_nop 0
	v_cvt_pk_bf16_f32 v229, v56, v57
	s_nop 0
	global_load_dword v54, v[74:75], off
	v_add_u32_e32 v56, 0x90, v144
	v_ashrrev_i32_e32 v57, 31, v56
	v_lshl_add_u64 v[58:59], v[56:57], 2, s[12:13]
	s_waitcnt vmcnt(0)
	v_pk_mul_f32 v[46:47], v[46:47], v[54:55] op_sel_hi:[1,0]
	v_pk_mul_f32 v[48:49], v[48:49], v[54:55] op_sel_hi:[1,0]
	v_cvt_pk_bf16_f32 v230, v46, v47
	s_nop 0
	v_cvt_pk_bf16_f32 v231, v48, v49
	s_nop 1
	v_permlane16_swap_b32_e32 v228, v230
	v_permlane16_swap_b32_e32 v229, v231
	v_lshl_add_u64 v[232:233], v[68:69], 0, v[234:235]
	global_store_dwordx4 v[232:233], v[228:231], off offset:256
	global_load_dword v46, v[58:59], off
	v_mad_i64_i32 v[48:49], s[0:1], v56, s52, v[146:147]
	v_lshl_add_u64 v[48:49], v[48:49], 0, s[26:27]
	v_lshl_add_u64 v[48:49], v[48:49], 0, v[134:135]
	s_waitcnt vmcnt(0)
	v_pk_mul_f32 v[52:53], v[52:53], v[46:47] op_sel_hi:[1,0]
	v_pk_mul_f32 v[46:47], v[50:51], v[46:47] op_sel_hi:[1,0]
	s_nop 0
	v_cvt_pk_bf16_f32 v224, v46, v47
	v_cvt_pk_bf16_f32 v225, v52, v53
	s_nop 0
	global_load_dword v46, v[58:59], off
	s_waitcnt vmcnt(0)
	v_pk_mul_f32 v[42:43], v[42:43], v[46:47] op_sel_hi:[1,0]
	v_pk_mul_f32 v[44:45], v[44:45], v[46:47] op_sel_hi:[1,0]
	v_cvt_pk_bf16_f32 v226, v42, v43
	s_nop 0
	v_cvt_pk_bf16_f32 v227, v44, v45
	s_nop 1
	v_permlane16_swap_b32_e32 v224, v226
	v_permlane16_swap_b32_e32 v225, v227
	v_lshl_add_u64 v[232:233], v[48:49], 0, v[234:235]
	global_store_dwordx4 v[232:233], v[224:227], off
	global_load_dword v42, v[58:59], off
	s_waitcnt vmcnt(0)
	v_pk_mul_f32 v[38:39], v[38:39], v[42:43] op_sel_hi:[1,0]
	v_pk_mul_f32 v[40:41], v[40:41], v[42:43] op_sel_hi:[1,0]
	v_cvt_pk_bf16_f32 v228, v38, v39
	s_nop 0
	v_cvt_pk_bf16_f32 v229, v40, v41
	s_nop 0
	global_load_dword v38, v[58:59], off
	v_add_u32_e32 v40, 0xa0, v144
	v_ashrrev_i32_e32 v41, 31, v40
	v_lshl_add_u64 v[42:43], v[40:41], 2, s[12:13]
	s_waitcnt vmcnt(0)
	v_pk_mul_f32 v[30:31], v[30:31], v[38:39] op_sel_hi:[1,0]
	v_pk_mul_f32 v[32:33], v[32:33], v[38:39] op_sel_hi:[1,0]
	v_cvt_pk_bf16_f32 v230, v30, v31
	s_nop 0
	v_cvt_pk_bf16_f32 v231, v32, v33
	s_nop 1
	v_permlane16_swap_b32_e32 v228, v230
	v_permlane16_swap_b32_e32 v229, v231
	v_lshl_add_u64 v[232:233], v[48:49], 0, v[234:235]
	global_store_dwordx4 v[232:233], v[228:231], off offset:256
	global_load_dword v30, v[42:43], off
	v_mad_i64_i32 v[32:33], s[0:1], v40, s52, v[146:147]
	v_lshl_add_u64 v[32:33], v[32:33], 0, s[26:27]
	v_lshl_add_u64 v[32:33], v[32:33], 0, v[134:135]
	s_waitcnt vmcnt(0)
	v_pk_mul_f32 v[36:37], v[36:37], v[30:31] op_sel_hi:[1,0]
	v_pk_mul_f32 v[30:31], v[34:35], v[30:31] op_sel_hi:[1,0]
	s_nop 0
	v_cvt_pk_bf16_f32 v224, v30, v31
	v_cvt_pk_bf16_f32 v225, v36, v37
	s_nop 0
	global_load_dword v30, v[42:43], off
	s_waitcnt vmcnt(0)
	v_pk_mul_f32 v[26:27], v[26:27], v[30:31] op_sel_hi:[1,0]
	v_pk_mul_f32 v[28:29], v[28:29], v[30:31] op_sel_hi:[1,0]
	v_cvt_pk_bf16_f32 v226, v26, v27
	s_nop 0
	v_cvt_pk_bf16_f32 v227, v28, v29
	s_nop 1
	v_permlane16_swap_b32_e32 v224, v226
	v_permlane16_swap_b32_e32 v225, v227
	v_lshl_add_u64 v[232:233], v[32:33], 0, v[234:235]
	global_store_dwordx4 v[232:233], v[224:227], off
	global_load_dword v26, v[42:43], off
	s_waitcnt vmcnt(0)
	v_pk_mul_f32 v[22:23], v[22:23], v[26:27] op_sel_hi:[1,0]
	v_pk_mul_f32 v[24:25], v[24:25], v[26:27] op_sel_hi:[1,0]
	v_cvt_pk_bf16_f32 v228, v22, v23
	s_nop 0
	v_cvt_pk_bf16_f32 v229, v24, v25
	s_nop 0
	global_load_dword v22, v[42:43], off
	v_add_u32_e32 v24, 0xb0, v144
	v_ashrrev_i32_e32 v25, 31, v24
	v_lshl_add_u64 v[26:27], v[24:25], 2, s[12:13]
	s_waitcnt vmcnt(0)
	v_pk_mul_f32 v[14:15], v[14:15], v[22:23] op_sel_hi:[1,0]
	v_pk_mul_f32 v[16:17], v[16:17], v[22:23] op_sel_hi:[1,0]
	v_cvt_pk_bf16_f32 v230, v14, v15
	s_nop 0
	v_cvt_pk_bf16_f32 v231, v16, v17
	s_nop 1
	v_permlane16_swap_b32_e32 v228, v230
	v_permlane16_swap_b32_e32 v229, v231
	v_lshl_add_u64 v[232:233], v[32:33], 0, v[234:235]
	global_store_dwordx4 v[232:233], v[228:231], off offset:256
	global_load_dword v14, v[26:27], off
	v_mad_i64_i32 v[16:17], s[0:1], v24, s52, v[146:147]
	v_lshl_add_u64 v[16:17], v[16:17], 0, s[26:27]
	v_lshl_add_u64 v[16:17], v[16:17], 0, v[134:135]
	s_waitcnt vmcnt(0)
	v_pk_mul_f32 v[20:21], v[20:21], v[14:15] op_sel_hi:[1,0]
	v_pk_mul_f32 v[14:15], v[18:19], v[14:15] op_sel_hi:[1,0]
	s_nop 0
	v_cvt_pk_bf16_f32 v224, v14, v15
	v_cvt_pk_bf16_f32 v225, v20, v21
	s_nop 0
	global_load_dword v14, v[26:27], off
	s_waitcnt vmcnt(0)
	v_pk_mul_f32 v[10:11], v[10:11], v[14:15] op_sel_hi:[1,0]
	v_pk_mul_f32 v[12:13], v[12:13], v[14:15] op_sel_hi:[1,0]
	v_cvt_pk_bf16_f32 v226, v10, v11
	s_nop 0
	v_cvt_pk_bf16_f32 v227, v12, v13
	s_nop 1
	v_permlane16_swap_b32_e32 v224, v226
	v_permlane16_swap_b32_e32 v225, v227
	v_lshl_add_u64 v[232:233], v[16:17], 0, v[234:235]
	global_store_dwordx4 v[232:233], v[224:227], off
	global_load_dword v10, v[26:27], off
	s_waitcnt vmcnt(0)
	v_pk_mul_f32 v[6:7], v[6:7], v[10:11] op_sel_hi:[1,0]
	v_pk_mul_f32 v[8:9], v[8:9], v[10:11] op_sel_hi:[1,0]
	v_cvt_pk_bf16_f32 v228, v6, v7
	s_nop 0
	v_cvt_pk_bf16_f32 v229, v8, v9
	s_nop 0
	global_load_dword v6, v[26:27], off
	s_waitcnt vmcnt(0)
	v_pk_mul_f32 v[2:3], v[2:3], v[6:7] op_sel_hi:[1,0]
	v_pk_mul_f32 v[4:5], v[4:5], v[6:7] op_sel_hi:[1,0]
	v_cvt_pk_bf16_f32 v230, v2, v3
	s_nop 0
	v_cvt_pk_bf16_f32 v231, v4, v5
	s_nop 1
	v_permlane16_swap_b32_e32 v228, v230
	v_permlane16_swap_b32_e32 v229, v231
	v_lshl_add_u64 v[232:233], v[16:17], 0, v[234:235]
	global_store_dwordx4 v[232:233], v[228:231], off offset:256
	s_cbranch_vccnz .LBB0_2694
	s_andn2_b64 vcc, exec, s[8:9]
	s_cbranch_vccnz .LBB0_2693
	s_barrier
	s_branch .LBB0_2693
